# v73 + latent attention loop: tile barrier after the row sums, the 16 copies of -m replaced by MFMA C operands, the two NaN-canonicalising self-max ops per q-block chain removed
# baseline (speedup 1.0000x reference)
.LBB0_362:
	s_and_b32 s14, s11, 1
	s_mul_i32 s12, s14, 0x4600
	s_add_i32 s15, s12, 16
	v_add3_u32 v160, s15, v209, v214
	ds_read_b128 v[96:99], v160
	ds_read_b128 v[224:227], v160 offset:4608
	ds_read_b128 v[228:231], v160 offset:32
	ds_read_b128 v[232:235], v160 offset:4640
	ds_read_b128 v[240:243], v160 offset:64
	ds_read_b128 v[248:251], v160 offset:4672
	s_waitcnt lgkmcnt(5)
	v_mfma_f32_32x32x16_bf16 v[144:159], v[96:99], v[162:165], v[48:63]
	v_mfma_f32_32x32x16_bf16 v[128:143], v[96:99], v[166:169], v[80:95]
	s_waitcnt lgkmcnt(4)
	v_mfma_f32_32x32x16_bf16 v[112:127], v[224:227], v[162:165], v[48:63]
	s_nop 0
	v_mfma_f32_32x32x16_bf16 v[96:111], v[224:227], v[166:169], v[80:95]
	ds_read_b128 v[224:227], v160 offset:96
	s_waitcnt lgkmcnt(4)
	v_mfma_f32_32x32x16_bf16 v[144:159], v[228:231], v[170:173], v[144:159]
	s_waitcnt lgkmcnt(3)
	v_mfma_f32_32x32x16_bf16 v[112:127], v[232:235], v[170:173], v[112:127]
	v_mfma_f32_32x32x16_bf16 v[128:143], v[228:231], v[174:177], v[128:143]
	v_mfma_f32_32x32x16_bf16 v[96:111], v[232:235], v[174:177], v[96:111]
	ds_read_b128 v[228:231], v160 offset:4704
	s_waitcnt lgkmcnt(3)
	v_mfma_f32_32x32x16_bf16 v[144:159], v[240:243], v[178:181], v[144:159]
	s_waitcnt lgkmcnt(2)
	v_mfma_f32_32x32x16_bf16 v[112:127], v[248:251], v[178:181], v[112:127]
	v_mfma_f32_32x32x16_bf16 v[128:143], v[240:243], v[186:189], v[128:143]
	v_mfma_f32_32x32x16_bf16 v[96:111], v[248:251], v[186:189], v[96:111]
	v_add3_u32 v240, s15, v211, v210
	v_add_u32_e32 v241, 0x3000, v240
	v_add_u32_e32 v240, 0x2000, v240
	ds_read2_b64 v[232:235], v240 offset0:128 offset1:130
	ds_read2_b64 v[248:251], v241 offset0:160 offset1:162
	s_waitcnt lgkmcnt(3)
	v_mfma_f32_32x32x16_bf16 v[144:159], v[224:227], v[182:185], v[144:159]
	s_waitcnt lgkmcnt(2)
	v_mfma_f32_32x32x16_bf16 v[112:127], v[228:231], v[182:185], v[112:127]
	s_nop 9
	v_max_f32_e32 v160, v145, v145
	v_max_f32_e32 v215, v144, v144
	v_max_f32_e32 v160, v215, v160
	v_mfma_f32_32x32x16_bf16 v[128:143], v[224:227], v[190:193], v[128:143]
	v_max3_f32 v215, v146, v147, v113
	v_max3_f32 v160, v160, v112, v114
	v_max3_f32 v160, v160, v115, v148
	v_max3_f32 v215, v215, v150, v151
	v_max3_f32 v160, v160, v149, v116
	v_max3_f32 v215, v215, v118, v119
	v_max3_f32 v160, v160, v117, v152
	v_max3_f32 v215, v215, v154, v155
	v_max3_f32 v160, v160, v153, v120
	v_max3_f32 v215, v215, v122, v123
	v_mfma_f32_32x32x16_bf16 v[96:111], v[228:231], v[190:193], v[96:111]
	v_max3_f32 v160, v160, v121, v156
	v_max3_f32 v215, v215, v158, v159
	v_max3_f32 v160, v160, v157, v124
	v_max3_f32 v215, v215, v126, v127
	v_max3_f32 v160, v160, v125, v215
	v_mov_b32_e32 v215, v160
	s_nop 1
	v_permlane32_swap_b32_e32 v160, v215
	v_max_f32_e32 v160, v160, v215
	v_cmp_lt_f32_e32 vcc, s17, v160
	s_cbranch_vccz .LBB0_364
	v_max_f32_e32 v48, v160, v160
	v_max_f32_e32 v50, 0, v48
	v_exp_f32_e64 v51, -v50
	s_nop 0
	v_pk_add_f32 v[52:53], v[216:217], v[50:51]
	v_pk_mul_f32 v[48:49], v[216:217], v[50:51]
	v_pk_add_f32 v[144:145], v[144:145], v[50:51] op_sel_hi:[1,0] neg_lo:[0,1] neg_hi:[0,1]
	v_mov_b32_e32 v53, v49
	v_pk_add_f32 v[112:113], v[112:113], v[50:51] op_sel_hi:[1,0] neg_lo:[0,1] neg_hi:[0,1]
	v_pk_add_f32 v[48:49], v[52:53], 0 neg_lo:[1,1] neg_hi:[1,1]
	v_pk_add_f32 v[146:147], v[146:147], v[50:51] op_sel_hi:[1,0] neg_lo:[0,1] neg_hi:[0,1]
	v_pk_add_f32 v[114:115], v[114:115], v[50:51] op_sel_hi:[1,0] neg_lo:[0,1] neg_hi:[0,1]
	v_pk_add_f32 v[148:149], v[148:149], v[50:51] op_sel_hi:[1,0] neg_lo:[0,1] neg_hi:[0,1]
	v_pk_add_f32 v[116:117], v[116:117], v[50:51] op_sel_hi:[1,0] neg_lo:[0,1] neg_hi:[0,1]
	v_pk_add_f32 v[150:151], v[150:151], v[50:51] op_sel_hi:[1,0] neg_lo:[0,1] neg_hi:[0,1]
	v_pk_add_f32 v[118:119], v[118:119], v[50:51] op_sel_hi:[1,0] neg_lo:[0,1] neg_hi:[0,1]
	v_pk_add_f32 v[152:153], v[152:153], v[50:51] op_sel_hi:[1,0] neg_lo:[0,1] neg_hi:[0,1]
	v_pk_add_f32 v[120:121], v[120:121], v[50:51] op_sel_hi:[1,0] neg_lo:[0,1] neg_hi:[0,1]
	v_pk_add_f32 v[154:155], v[154:155], v[50:51] op_sel_hi:[1,0] neg_lo:[0,1] neg_hi:[0,1]
	v_pk_add_f32 v[122:123], v[122:123], v[50:51] op_sel_hi:[1,0] neg_lo:[0,1] neg_hi:[0,1]
	v_pk_add_f32 v[156:157], v[156:157], v[50:51] op_sel_hi:[1,0] neg_lo:[0,1] neg_hi:[0,1]
	v_pk_add_f32 v[124:125], v[124:125], v[50:51] op_sel_hi:[1,0] neg_lo:[0,1] neg_hi:[0,1]
	v_pk_add_f32 v[158:159], v[158:159], v[50:51] op_sel_hi:[1,0] neg_lo:[0,1] neg_hi:[0,1]
	v_pk_add_f32 v[126:127], v[126:127], v[50:51] op_sel_hi:[1,0] neg_lo:[0,1] neg_hi:[0,1]
	v_mov_b32_e32 v50, v51
	v_pk_mul_f32 v[78:79], v[78:79], v[50:51] op_sel_hi:[1,0]
	v_pk_mul_f32 v[76:77], v[76:77], v[50:51] op_sel_hi:[1,0]
	v_pk_mul_f32 v[74:75], v[74:75], v[50:51] op_sel_hi:[1,0]
	v_pk_mul_f32 v[72:73], v[72:73], v[50:51] op_sel_hi:[1,0]
	v_pk_mul_f32 v[70:71], v[70:71], v[50:51] op_sel_hi:[1,0]
	v_pk_mul_f32 v[68:69], v[68:69], v[50:51] op_sel_hi:[1,0]
	v_pk_mul_f32 v[66:67], v[66:67], v[50:51] op_sel_hi:[1,0]
	v_pk_mul_f32 v[64:65], v[64:65], v[50:51] op_sel_hi:[1,0]
	v_pk_mul_f32 v[14:15], v[14:15], v[50:51] op_sel_hi:[1,0]
	v_pk_mul_f32 v[12:13], v[12:13], v[50:51] op_sel_hi:[1,0]
	v_pk_mul_f32 v[10:11], v[10:11], v[50:51] op_sel_hi:[1,0]
	v_pk_mul_f32 v[8:9], v[8:9], v[50:51] op_sel_hi:[1,0]
	v_pk_mul_f32 v[6:7], v[6:7], v[50:51] op_sel_hi:[1,0]
	v_pk_mul_f32 v[4:5], v[4:5], v[50:51] op_sel_hi:[1,0]
	v_pk_mul_f32 v[2:3], v[2:3], v[50:51] op_sel_hi:[1,0]
	v_pk_mul_f32 v[0:1], v[0:1], v[50:51] op_sel_hi:[1,0]
	v_mov_b64_e32 v[216:217], v[52:53]
	v_mov_b32_e32 v49, v48
	v_mov_b32_e32 v50, v48
	v_mov_b32_e32 v51, v48
	v_mov_b32_e32 v52, v48
	v_mov_b32_e32 v53, v48
	v_mov_b32_e32 v54, v48
	v_mov_b32_e32 v55, v48
	v_mov_b32_e32 v56, v48
	v_mov_b32_e32 v57, v48
	v_mov_b32_e32 v58, v48
	v_mov_b32_e32 v59, v48
	v_mov_b32_e32 v60, v48
	v_mov_b32_e32 v61, v48
	v_mov_b32_e32 v62, v48
	v_mov_b32_e32 v63, v48
.LBB0_364:
	v_max_f32_e32 v160, v129, v129
	v_max_f32_e32 v215, v128, v128
	v_max_f32_e32 v160, v215, v160
	v_max3_f32 v215, v130, v131, v97
	v_max3_f32 v160, v160, v96, v98
	v_max3_f32 v160, v160, v99, v132
	v_max3_f32 v215, v215, v134, v135
	v_max3_f32 v160, v160, v133, v100
	v_max3_f32 v215, v215, v102, v103
	v_max3_f32 v160, v160, v101, v136
	v_max3_f32 v215, v215, v138, v139
	v_max3_f32 v160, v160, v137, v104
	v_max3_f32 v215, v215, v106, v107
	v_max3_f32 v160, v160, v105, v140
	v_max3_f32 v215, v215, v142, v143
	v_max3_f32 v160, v160, v141, v108
	v_max3_f32 v215, v215, v110, v111
	v_max3_f32 v160, v160, v109, v215
	v_mov_b32_e32 v215, v160
	s_nop 1
	v_permlane32_swap_b32_e32 v160, v215
	v_max_f32_e32 v160, v160, v215
	v_cmp_lt_f32_e32 vcc, s17, v160
	s_cbranch_vccz .LBB0_366
	v_max_f32_e32 v80, v160, v160
	v_max_f32_e32 v82, 0, v80
	v_exp_f32_e64 v83, -v82
	s_nop 0
	v_pk_add_f32 v[84:85], v[222:223], v[82:83]
	v_pk_mul_f32 v[80:81], v[222:223], v[82:83]
	v_pk_add_f32 v[128:129], v[128:129], v[82:83] op_sel_hi:[1,0] neg_lo:[0,1] neg_hi:[0,1]
	v_mov_b32_e32 v85, v81
	v_pk_add_f32 v[96:97], v[96:97], v[82:83] op_sel_hi:[1,0] neg_lo:[0,1] neg_hi:[0,1]
	v_pk_add_f32 v[80:81], v[84:85], 0 neg_lo:[1,1] neg_hi:[1,1]
	v_pk_add_f32 v[130:131], v[130:131], v[82:83] op_sel_hi:[1,0] neg_lo:[0,1] neg_hi:[0,1]
	v_pk_add_f32 v[98:99], v[98:99], v[82:83] op_sel_hi:[1,0] neg_lo:[0,1] neg_hi:[0,1]
	v_pk_add_f32 v[132:133], v[132:133], v[82:83] op_sel_hi:[1,0] neg_lo:[0,1] neg_hi:[0,1]
	v_pk_add_f32 v[100:101], v[100:101], v[82:83] op_sel_hi:[1,0] neg_lo:[0,1] neg_hi:[0,1]
	v_pk_add_f32 v[134:135], v[134:135], v[82:83] op_sel_hi:[1,0] neg_lo:[0,1] neg_hi:[0,1]
	v_pk_add_f32 v[102:103], v[102:103], v[82:83] op_sel_hi:[1,0] neg_lo:[0,1] neg_hi:[0,1]
	v_pk_add_f32 v[136:137], v[136:137], v[82:83] op_sel_hi:[1,0] neg_lo:[0,1] neg_hi:[0,1]
	v_pk_add_f32 v[104:105], v[104:105], v[82:83] op_sel_hi:[1,0] neg_lo:[0,1] neg_hi:[0,1]
	v_pk_add_f32 v[138:139], v[138:139], v[82:83] op_sel_hi:[1,0] neg_lo:[0,1] neg_hi:[0,1]
	v_pk_add_f32 v[106:107], v[106:107], v[82:83] op_sel_hi:[1,0] neg_lo:[0,1] neg_hi:[0,1]
	v_pk_add_f32 v[140:141], v[140:141], v[82:83] op_sel_hi:[1,0] neg_lo:[0,1] neg_hi:[0,1]
	v_pk_add_f32 v[108:109], v[108:109], v[82:83] op_sel_hi:[1,0] neg_lo:[0,1] neg_hi:[0,1]
	v_pk_add_f32 v[142:143], v[142:143], v[82:83] op_sel_hi:[1,0] neg_lo:[0,1] neg_hi:[0,1]
	v_pk_add_f32 v[110:111], v[110:111], v[82:83] op_sel_hi:[1,0] neg_lo:[0,1] neg_hi:[0,1]
	v_mov_b32_e32 v82, v83
	v_pk_mul_f32 v[46:47], v[46:47], v[82:83] op_sel_hi:[1,0]
	v_pk_mul_f32 v[44:45], v[44:45], v[82:83] op_sel_hi:[1,0]
	v_pk_mul_f32 v[42:43], v[42:43], v[82:83] op_sel_hi:[1,0]
	v_pk_mul_f32 v[40:41], v[40:41], v[82:83] op_sel_hi:[1,0]
	v_pk_mul_f32 v[38:39], v[38:39], v[82:83] op_sel_hi:[1,0]
	v_pk_mul_f32 v[36:37], v[36:37], v[82:83] op_sel_hi:[1,0]
	v_pk_mul_f32 v[34:35], v[34:35], v[82:83] op_sel_hi:[1,0]
	v_pk_mul_f32 v[32:33], v[32:33], v[82:83] op_sel_hi:[1,0]
	v_pk_mul_f32 v[30:31], v[30:31], v[82:83] op_sel_hi:[1,0]
	v_pk_mul_f32 v[28:29], v[28:29], v[82:83] op_sel_hi:[1,0]
	v_pk_mul_f32 v[26:27], v[26:27], v[82:83] op_sel_hi:[1,0]
	v_pk_mul_f32 v[24:25], v[24:25], v[82:83] op_sel_hi:[1,0]
	v_pk_mul_f32 v[22:23], v[22:23], v[82:83] op_sel_hi:[1,0]
	v_pk_mul_f32 v[20:21], v[20:21], v[82:83] op_sel_hi:[1,0]
	v_pk_mul_f32 v[18:19], v[18:19], v[82:83] op_sel_hi:[1,0]
	v_pk_mul_f32 v[16:17], v[16:17], v[82:83] op_sel_hi:[1,0]
	v_mov_b64_e32 v[222:223], v[84:85]
	v_mov_b32_e32 v81, v80
	v_mov_b32_e32 v82, v80
	v_mov_b32_e32 v83, v80
	v_mov_b32_e32 v84, v80
	v_mov_b32_e32 v85, v80
	v_mov_b32_e32 v86, v80
	v_mov_b32_e32 v87, v80
	v_mov_b32_e32 v88, v80
	v_mov_b32_e32 v89, v80
	v_mov_b32_e32 v90, v80
	v_mov_b32_e32 v91, v80
	v_mov_b32_e32 v92, v80
	v_mov_b32_e32 v93, v80
	v_mov_b32_e32 v94, v80
	v_mov_b32_e32 v95, v80
